# fused branch-merge GEMM final epilogue: gate-load waits re-derived per first consumer (counted)
# baseline (speedup 1.0000x reference)
; __device__ __forceinline__ unsigned cvt_pk_bf16(float lo, float hi) { const f2_t_ v = {lo, hi}; return __builtin_bit_cast(unsigned, __builtin_convertvector(v, bf2_t_)); }
;     static __device__ __forceinline__ void unpack(const u32x4 g4, f32x4& g0, f32x4& g1) { g0 = (f32x4){bflo(g4.x), bfhi(g4.x), bflo(g4.y), bfhi(g4.y)}; g1 = (f32x4){bflo(g4.z), bfhi(g4.z), bflo(g4.w), bfhi(g4.w)}; }
;     __device__ __forceinline__ void operator()(const f32x4 (&acc)[2][2][4][2], const Unit& u, int wr, int wc, int fr, int fq) const {
;     ...
;         u32x4 gw[2][2];
; #pragma unroll
;         for (int bj = 0; bj < 2; ++bj) gw[0][bj] = *(const u32x4*)(GT + r0 * ldg + 4096 + col0 + bj * HALF);
; #pragma unroll
;         for (int gi = 0; gi < 8; ++gi) {
;             const int ai = gi >> 2, m = gi & 3; const size_t row = r0 + ai * HALF + m * 16;
;             if (gi < 7) { const size_t row2 = r0 + ((gi + 1) >> 2) * HALF + ((gi + 1) & 3) * 16;
; #pragma unroll
;                 for (int bj = 0; bj < 2; ++bj) gw[(gi + 1) & 1][bj] = *(const u32x4*)(GT + row2 * ldg + 4096 + col0 + bj * HALF); }
;             asm volatile("" ::: "memory");
; #pragma unroll
;             for (int bj = 0; bj < 2; ++bj) {
;                 f32x4 g0, g1; unpack(gw[gi & 1][bj], g0, g1);
;                 f32x4 v0, v1;
; #pragma unroll
;                 for (int j = 0; j < 4; ++j) { v0[j] = acc[ai][bj][m][0][j] * fmaxf(g0[j], 1e-20f); v1[j] = acc[ai][bj][m][1][j] * fmaxf(g1[j], 1e-20f); }
;                 u32x4 w; w.x = cvt_pk_bf16(v0[0], v0[1]); w.y = cvt_pk_bf16(v0[2], v0[3]); w.z = cvt_pk_bf16(v1[0], v1[1]); w.w = cvt_pk_bf16(v1[2], v1[3]);
;                 *(u32x4*)(O + row * 2048 + col0 + bj * HALF) = w;
;             }
.LBB0_998:
	v_mov_b64_e32 v[146:147], s[16:17]
	v_ashrrev_i32_e32 v187, 31, v186
	v_mad_i64_i32 v[134:135], s[26:27], v184, s83, v[146:147]
	v_lshlrev_b64 v[4:5], 1, v[186:187]
	v_lshl_add_u64 v[150:151], v[134:135], 0, v[4:5]
	v_add_co_u32_e32 v136, vcc, 0x2000, v150
	s_mov_b64 s[28:29], 0x2000
	s_nop 0
	v_addc_co_u32_e32 v137, vcc, 0, v151, vcc
	v_lshl_add_u64 v[134:135], v[150:151], 0, s[28:29]
	global_load_dwordx4 v[152:155], v[136:137], off
	global_load_dwordx4 v[142:145], v[134:135], off offset:256
	s_mov_b64 s[30:31], 0x32000
	v_add_co_u32_e32 v136, vcc, 0x32000, v150
	v_lshl_add_u64 v[134:135], v[150:151], 0, s[30:31]
	s_nop 0
	v_addc_co_u32_e32 v137, vcc, 0, v151, vcc
	global_load_dwordx4 v[138:141], v[136:137], off
	s_nop 0
	global_load_dwordx4 v[134:137], v[134:135], off offset:256
	v_ashrrev_i32_e32 v185, 31, v184
	v_lshlrev_b64 v[148:149], 12, v[184:185]
	s_mov_b64 s[60:61], 0x62000
	s_mov_b64 s[26:27], 0x92000
	s_waitcnt vmcnt(3)
	v_lshlrev_b32_e32 v3, 16, v152
	v_lshlrev_b32_e32 v157, 16, v153
	v_and_b32_e32 v158, 0xffff0000, v153
	v_lshlrev_b32_e32 v153, 16, v154
	v_max_f32_e32 v3, v3, v3
	v_and_b32_e32 v156, 0xffff0000, v152
	v_max_f32_e32 v152, 0x1e3ce508, v3
	v_max_f32_e32 v3, v153, v153
	v_and_b32_e32 v159, 0xffff0000, v154
	v_max_f32_e32 v154, 0x1e3ce508, v3
	v_max_f32_e32 v3, v156, v156
	v_max_f32_e32 v153, 0x1e3ce508, v3
	v_max_f32_e32 v3, v159, v159
	v_lshlrev_b32_e32 v160, 16, v155
	v_and_b32_e32 v161, 0xffff0000, v155
	v_max_f32_e32 v155, 0x1e3ce508, v3
	v_max_f32_e32 v3, v157, v157
	v_pk_mul_f32 v[126:127], v[126:127], v[152:153]
	v_max_f32_e32 v152, 0x1e3ce508, v3
	v_max_f32_e32 v3, v160, v160
	v_pk_mul_f32 v[130:131], v[130:131], v[154:155]
	v_max_f32_e32 v154, 0x1e3ce508, v3
	v_max_f32_e32 v3, v158, v158
	v_max_f32_e32 v153, 0x1e3ce508, v3
	v_max_f32_e32 v3, v161, v161
	v_max_f32_e32 v155, 0x1e3ce508, v3
	v_pk_mul_f32 v[152:153], v[128:129], v[152:153]
	v_pk_mul_f32 v[132:133], v[132:133], v[154:155]
	v_cvt_pk_bf16_f32 v128, v126, v127
	v_lshl_add_u64 v[126:127], s[18:19], 0, v[148:149]
	v_cvt_pk_bf16_f32 v129, v152, v153
	v_cvt_pk_bf16_f32 v130, v130, v131
	v_cvt_pk_bf16_f32 v131, v132, v133
	v_lshl_add_u64 v[126:127], v[126:127], 0, v[4:5]
	s_waitcnt vmcnt(2)
	v_lshlrev_b32_e32 v3, 16, v142
	global_store_dwordx4 v[126:127], v[128:131], off
	v_max_f32_e32 v3, v3, v3
	v_lshlrev_b32_e32 v132, 16, v143
	v_lshlrev_b32_e32 v130, 16, v144
	v_and_b32_e32 v129, 0xffff0000, v142
	v_max_f32_e32 v128, 0x1e3ce508, v3
	v_max_f32_e32 v3, v130, v130
	v_and_b32_e32 v131, 0xffff0000, v144
	v_max_f32_e32 v130, 0x1e3ce508, v3
	v_max_f32_e32 v3, v129, v129
	v_max_f32_e32 v129, 0x1e3ce508, v3
	v_max_f32_e32 v3, v131, v131
	v_lshlrev_b32_e32 v142, 16, v145
	v_max_f32_e32 v131, 0x1e3ce508, v3
	v_max_f32_e32 v3, v132, v132
	v_and_b32_e32 v133, 0xffff0000, v143
	v_pk_mul_f32 v[122:123], v[122:123], v[128:129]
	v_pk_mul_f32 v[128:129], v[118:119], v[130:131]
	v_max_f32_e32 v118, 0x1e3ce508, v3
	v_max_f32_e32 v3, v142, v142
	v_and_b32_e32 v143, 0xffff0000, v145
	v_max_f32_e32 v130, 0x1e3ce508, v3
	v_max_f32_e32 v3, v133, v133
	v_max_f32_e32 v119, 0x1e3ce508, v3
	v_max_f32_e32 v3, v143, v143
	v_max_f32_e32 v131, 0x1e3ce508, v3
	v_pk_mul_f32 v[124:125], v[124:125], v[118:119]
	v_pk_mul_f32 v[130:131], v[120:121], v[130:131]
	v_cvt_pk_bf16_f32 v118, v122, v123
	v_cvt_pk_bf16_f32 v119, v124, v125
	v_cvt_pk_bf16_f32 v120, v128, v129
	v_cvt_pk_bf16_f32 v121, v130, v131
	s_waitcnt vmcnt(2)
	v_lshlrev_b32_e32 v3, 16, v138
	global_store_dwordx4 v[126:127], v[118:121], off offset:256
	v_lshlrev_b32_e32 v130, 16, v140
	v_max_f32_e32 v3, v3, v3
	v_add_co_u32_e32 v118, vcc, s73, v150
	v_lshl_add_u64 v[122:123], v[150:151], 0, s[60:61]
	s_nop 0
	v_addc_co_u32_e32 v119, vcc, 0, v151, vcc
	v_and_b32_e32 v129, 0xffff0000, v138
	v_max_f32_e32 v128, 0x1e3ce508, v3
	v_max_f32_e32 v3, v130, v130
	global_load_dwordx4 v[118:121], v[118:119], off
	s_nop 0
	global_load_dwordx4 v[122:125], v[122:123], off offset:256
	v_and_b32_e32 v131, 0xffff0000, v140
	v_max_f32_e32 v130, 0x1e3ce508, v3
	v_max_f32_e32 v3, v129, v129
	v_lshlrev_b32_e32 v132, 16, v139
	v_max_f32_e32 v129, 0x1e3ce508, v3
	v_max_f32_e32 v3, v131, v131
	v_lshlrev_b32_e32 v138, 16, v141
	v_max_f32_e32 v131, 0x1e3ce508, v3
	v_max_f32_e32 v3, v132, v132
	v_and_b32_e32 v133, 0xffff0000, v139
	v_pk_mul_f32 v[114:115], v[114:115], v[128:129]
	v_pk_mul_f32 v[128:129], v[110:111], v[130:131]
	v_max_f32_e32 v110, 0x1e3ce508, v3
	v_max_f32_e32 v3, v138, v138
	v_and_b32_e32 v139, 0xffff0000, v141
	v_max_f32_e32 v130, 0x1e3ce508, v3
	v_max_f32_e32 v3, v133, v133
	v_max_f32_e32 v111, 0x1e3ce508, v3
	v_max_f32_e32 v3, v139, v139
	v_or_b32_e32 v126, 0x10000, v148
	v_mov_b32_e32 v127, v149
	v_max_f32_e32 v131, 0x1e3ce508, v3
	v_pk_mul_f32 v[116:117], v[116:117], v[110:111]
	v_pk_mul_f32 v[130:131], v[112:113], v[130:131]
	v_cvt_pk_bf16_f32 v110, v114, v115
	v_lshl_add_u64 v[114:115], s[18:19], 0, v[126:127]
	v_cvt_pk_bf16_f32 v111, v116, v117
	v_cvt_pk_bf16_f32 v112, v128, v129
	v_cvt_pk_bf16_f32 v113, v130, v131
	v_lshl_add_u64 v[114:115], v[114:115], 0, v[4:5]
	s_waitcnt vmcnt(4)
; __device__ __forceinline__ unsigned cvt_pk_bf16(float lo, float hi) { const f2_t_ v = {lo, hi}; return __builtin_bit_cast(unsigned, __builtin_convertvector(v, bf2_t_)); }
;     static __device__ __forceinline__ void unpack(const u32x4 g4, f32x4& g0, f32x4& g1) { g0 = (f32x4){bflo(g4.x), bfhi(g4.x), bflo(g4.y), bfhi(g4.y)}; g1 = (f32x4){bflo(g4.z), bfhi(g4.z), bflo(g4.w), bfhi(g4.w)}; }
;     __device__ __forceinline__ void operator()(const f32x4 (&acc)[2][2][4][2], const Unit& u, int wr, int wc, int fr, int fq) const {
;     ...
;             if (gi < 7) { const size_t row2 = r0 + ((gi + 1) >> 2) * HALF + ((gi + 1) & 3) * 16;
; #pragma unroll
;                 for (int bj = 0; bj < 2; ++bj) gw[(gi + 1) & 1][bj] = *(const u32x4*)(GT + row2 * ldg + 4096 + col0 + bj * HALF); }
;             asm volatile("" ::: "memory");
; #pragma unroll
;             for (int bj = 0; bj < 2; ++bj) {
;                 f32x4 g0, g1; unpack(gw[gi & 1][bj], g0, g1);
;                 f32x4 v0, v1;
; #pragma unroll
;                 for (int j = 0; j < 4; ++j) { v0[j] = acc[ai][bj][m][0][j] * fmaxf(g0[j], 1e-20f); v1[j] = acc[ai][bj][m][1][j] * fmaxf(g1[j], 1e-20f); }
;                 u32x4 w; w.x = cvt_pk_bf16(v0[0], v0[1]); w.y = cvt_pk_bf16(v0[2], v0[3]); w.z = cvt_pk_bf16(v1[0], v1[1]); w.w = cvt_pk_bf16(v1[2], v1[3]);
;                 *(u32x4*)(O + row * 2048 + col0 + bj * HALF) = w;
;             }
	v_lshlrev_b32_e32 v3, 16, v134
	global_store_dwordx4 v[114:115], v[110:113], off
	v_max_f32_e32 v3, v3, v3
	v_lshlrev_b32_e32 v116, 16, v135
	v_lshlrev_b32_e32 v112, 16, v136
	v_and_b32_e32 v111, 0xffff0000, v134
	v_max_f32_e32 v110, 0x1e3ce508, v3
	v_max_f32_e32 v3, v112, v112
	v_and_b32_e32 v113, 0xffff0000, v136
	v_max_f32_e32 v112, 0x1e3ce508, v3
	v_max_f32_e32 v3, v111, v111
	v_max_f32_e32 v111, 0x1e3ce508, v3
	v_max_f32_e32 v3, v113, v113
	v_lshlrev_b32_e32 v126, 16, v137
	v_max_f32_e32 v113, 0x1e3ce508, v3
	v_max_f32_e32 v3, v116, v116
	v_and_b32_e32 v117, 0xffff0000, v135
	v_pk_mul_f32 v[106:107], v[106:107], v[110:111]
	v_pk_mul_f32 v[110:111], v[102:103], v[112:113]
	v_max_f32_e32 v102, 0x1e3ce508, v3
	v_max_f32_e32 v3, v126, v126
	v_and_b32_e32 v127, 0xffff0000, v137
	v_max_f32_e32 v112, 0x1e3ce508, v3
	v_max_f32_e32 v3, v117, v117
	v_max_f32_e32 v103, 0x1e3ce508, v3
	v_max_f32_e32 v3, v127, v127
	v_max_f32_e32 v113, 0x1e3ce508, v3
	v_pk_mul_f32 v[108:109], v[108:109], v[102:103]
	v_pk_mul_f32 v[112:113], v[104:105], v[112:113]
	v_cvt_pk_bf16_f32 v102, v106, v107
	v_cvt_pk_bf16_f32 v103, v108, v109
	v_cvt_pk_bf16_f32 v104, v110, v111
	v_cvt_pk_bf16_f32 v105, v112, v113
	v_lshl_add_u64 v[106:107], v[150:151], 0, s[26:27]
	s_mov_b32 s26, 0x92000
	global_store_dwordx4 v[114:115], v[102:105], off offset:256
	v_or_b32_e32 v110, 0x20000, v148
	v_mov_b32_e32 v111, v149
	v_add_co_u32_e32 v102, vcc, s26, v150
	s_mov_b64 s[26:27], 0x182000
	s_nop 0
	v_addc_co_u32_e32 v103, vcc, 0, v151, vcc
	global_load_dwordx4 v[102:105], v[102:103], off
	s_nop 0
	global_load_dwordx4 v[106:109], v[106:107], off offset:256
	s_waitcnt vmcnt(5)
	v_lshlrev_b32_e32 v3, 16, v118
	v_lshlrev_b32_e32 v114, 16, v120
	v_max_f32_e32 v3, v3, v3
	v_and_b32_e32 v113, 0xffff0000, v118
	v_max_f32_e32 v112, 0x1e3ce508, v3
	v_max_f32_e32 v3, v114, v114
	v_and_b32_e32 v115, 0xffff0000, v120
	v_max_f32_e32 v114, 0x1e3ce508, v3
	v_max_f32_e32 v3, v113, v113
	v_lshlrev_b32_e32 v116, 16, v119
	v_max_f32_e32 v113, 0x1e3ce508, v3
	v_max_f32_e32 v3, v115, v115
	v_lshlrev_b32_e32 v118, 16, v121
	v_max_f32_e32 v115, 0x1e3ce508, v3
	v_max_f32_e32 v3, v116, v116
	v_and_b32_e32 v117, 0xffff0000, v119
	v_pk_mul_f32 v[98:99], v[98:99], v[112:113]
	v_pk_mul_f32 v[112:113], v[94:95], v[114:115]
	v_max_f32_e32 v94, 0x1e3ce508, v3
	v_max_f32_e32 v3, v118, v118
	v_and_b32_e32 v119, 0xffff0000, v121
	v_max_f32_e32 v114, 0x1e3ce508, v3
	v_max_f32_e32 v3, v117, v117
	v_max_f32_e32 v95, 0x1e3ce508, v3
	v_max_f32_e32 v3, v119, v119
	v_max_f32_e32 v115, 0x1e3ce508, v3
	v_pk_mul_f32 v[100:101], v[100:101], v[94:95]
	v_pk_mul_f32 v[114:115], v[96:97], v[114:115]
	v_cvt_pk_bf16_f32 v94, v98, v99
	v_lshl_add_u64 v[98:99], s[18:19], 0, v[110:111]
	v_cvt_pk_bf16_f32 v95, v100, v101
	v_cvt_pk_bf16_f32 v96, v112, v113
	v_cvt_pk_bf16_f32 v97, v114, v115
	v_lshl_add_u64 v[98:99], v[98:99], 0, v[4:5]
	s_waitcnt vmcnt(4)
	v_lshlrev_b32_e32 v3, 16, v122
	global_store_dwordx4 v[98:99], v[94:97], off
	v_max_f32_e32 v3, v3, v3
	v_lshlrev_b32_e32 v100, 16, v123
	v_lshlrev_b32_e32 v96, 16, v124
	v_and_b32_e32 v95, 0xffff0000, v122
	v_max_f32_e32 v94, 0x1e3ce508, v3
	v_max_f32_e32 v3, v96, v96
	v_and_b32_e32 v97, 0xffff0000, v124
	v_max_f32_e32 v96, 0x1e3ce508, v3
	v_max_f32_e32 v3, v95, v95
	v_max_f32_e32 v95, 0x1e3ce508, v3
	v_max_f32_e32 v3, v97, v97
	v_lshlrev_b32_e32 v110, 16, v125
	v_max_f32_e32 v97, 0x1e3ce508, v3
	v_max_f32_e32 v3, v100, v100
	v_and_b32_e32 v101, 0xffff0000, v123
	v_pk_mul_f32 v[90:91], v[90:91], v[94:95]
	v_pk_mul_f32 v[94:95], v[86:87], v[96:97]
	v_max_f32_e32 v86, 0x1e3ce508, v3
	v_max_f32_e32 v3, v110, v110
	v_and_b32_e32 v111, 0xffff0000, v125
	v_max_f32_e32 v96, 0x1e3ce508, v3
	v_max_f32_e32 v3, v101, v101
	v_max_f32_e32 v87, 0x1e3ce508, v3
	v_max_f32_e32 v3, v111, v111
	v_max_f32_e32 v97, 0x1e3ce508, v3
	v_pk_mul_f32 v[92:93], v[92:93], v[86:87]
	v_pk_mul_f32 v[96:97], v[88:89], v[96:97]
	v_cvt_pk_bf16_f32 v86, v90, v91
	v_cvt_pk_bf16_f32 v87, v92, v93
	v_cvt_pk_bf16_f32 v88, v94, v95
	v_cvt_pk_bf16_f32 v89, v96, v97
	global_store_dwordx4 v[98:99], v[86:89], off offset:256
	v_lshl_add_u64 v[90:91], v[150:151], 0, s[26:27]
	s_mov_b32 s26, 0x182000
	v_add_co_u32_e32 v86, vcc, s26, v150
	v_or_b32_e32 v94, 0x30000, v148
	s_nop 0
	v_addc_co_u32_e32 v87, vcc, 0, v151, vcc
	s_waitcnt vmcnt(3)
	v_lshlrev_b32_e32 v3, 16, v102
	v_lshlrev_b32_e32 v98, 16, v104
	v_max_f32_e32 v3, v3, v3
	v_and_b32_e32 v97, 0xffff0000, v102
	v_max_f32_e32 v96, 0x1e3ce508, v3
	v_max_f32_e32 v3, v98, v98
	v_and_b32_e32 v99, 0xffff0000, v104
	v_max_f32_e32 v98, 0x1e3ce508, v3
	v_max_f32_e32 v3, v97, v97
	v_lshlrev_b32_e32 v100, 16, v103
	v_max_f32_e32 v97, 0x1e3ce508, v3
	v_max_f32_e32 v3, v99, v99
	v_lshlrev_b32_e32 v102, 16, v105
	v_max_f32_e32 v99, 0x1e3ce508, v3
	v_max_f32_e32 v3, v100, v100
	global_load_dwordx4 v[86:89], v[86:87], off
	s_nop 0
	global_load_dwordx4 v[90:93], v[90:91], off offset:256
	v_and_b32_e32 v101, 0xffff0000, v103
	v_pk_mul_f32 v[82:83], v[82:83], v[96:97]
	v_pk_mul_f32 v[96:97], v[78:79], v[98:99]
	v_max_f32_e32 v78, 0x1e3ce508, v3
	v_max_f32_e32 v3, v102, v102
	v_and_b32_e32 v103, 0xffff0000, v105
	v_max_f32_e32 v98, 0x1e3ce508, v3
	v_max_f32_e32 v3, v101, v101
	v_max_f32_e32 v79, 0x1e3ce508, v3
	v_max_f32_e32 v3, v103, v103
	v_mov_b32_e32 v95, v149
	v_max_f32_e32 v99, 0x1e3ce508, v3
	v_pk_mul_f32 v[84:85], v[84:85], v[78:79]
	v_pk_mul_f32 v[98:99], v[80:81], v[98:99]
	v_cvt_pk_bf16_f32 v78, v82, v83
	v_lshl_add_u64 v[82:83], s[18:19], 0, v[94:95]
	v_cvt_pk_bf16_f32 v79, v84, v85
	v_cvt_pk_bf16_f32 v80, v96, v97
	v_cvt_pk_bf16_f32 v81, v98, v99
	v_lshl_add_u64 v[82:83], v[82:83], 0, v[4:5]
	s_waitcnt vmcnt(4)
; __device__ __forceinline__ unsigned cvt_pk_bf16(float lo, float hi) { const f2_t_ v = {lo, hi}; return __builtin_bit_cast(unsigned, __builtin_convertvector(v, bf2_t_)); }
;     static __device__ __forceinline__ void unpack(const u32x4 g4, f32x4& g0, f32x4& g1) { g0 = (f32x4){bflo(g4.x), bfhi(g4.x), bflo(g4.y), bfhi(g4.y)}; g1 = (f32x4){bflo(g4.z), bfhi(g4.z), bflo(g4.w), bfhi(g4.w)}; }
;     __device__ __forceinline__ void operator()(const f32x4 (&acc)[2][2][4][2], const Unit& u, int wr, int wc, int fr, int fq) const {
;     ...
;             if (gi < 7) { const size_t row2 = r0 + ((gi + 1) >> 2) * HALF + ((gi + 1) & 3) * 16;
; #pragma unroll
;                 for (int bj = 0; bj < 2; ++bj) gw[(gi + 1) & 1][bj] = *(const u32x4*)(GT + row2 * ldg + 4096 + col0 + bj * HALF); }
;             asm volatile("" ::: "memory");
; #pragma unroll
;             for (int bj = 0; bj < 2; ++bj) {
;                 f32x4 g0, g1; unpack(gw[gi & 1][bj], g0, g1);
;                 f32x4 v0, v1;
; #pragma unroll
;                 for (int j = 0; j < 4; ++j) { v0[j] = acc[ai][bj][m][0][j] * fmaxf(g0[j], 1e-20f); v1[j] = acc[ai][bj][m][1][j] * fmaxf(g1[j], 1e-20f); }
;                 u32x4 w; w.x = cvt_pk_bf16(v0[0], v0[1]); w.y = cvt_pk_bf16(v0[2], v0[3]); w.z = cvt_pk_bf16(v1[0], v1[1]); w.w = cvt_pk_bf16(v1[2], v1[3]);
;                 *(u32x4*)(O + row * 2048 + col0 + bj * HALF) = w;
;             }
	v_lshlrev_b32_e32 v3, 16, v106
	global_store_dwordx4 v[82:83], v[78:81], off
	v_max_f32_e32 v3, v3, v3
	v_lshlrev_b32_e32 v84, 16, v107
	v_lshlrev_b32_e32 v80, 16, v108
	v_and_b32_e32 v79, 0xffff0000, v106
	v_max_f32_e32 v78, 0x1e3ce508, v3
	v_max_f32_e32 v3, v80, v80
	v_and_b32_e32 v81, 0xffff0000, v108
	v_max_f32_e32 v80, 0x1e3ce508, v3
	v_max_f32_e32 v3, v79, v79
	v_max_f32_e32 v79, 0x1e3ce508, v3
	v_max_f32_e32 v3, v81, v81
	v_lshlrev_b32_e32 v94, 16, v109
	v_max_f32_e32 v81, 0x1e3ce508, v3
	v_max_f32_e32 v3, v84, v84
	v_and_b32_e32 v85, 0xffff0000, v107
	v_pk_mul_f32 v[74:75], v[74:75], v[78:79]
	v_pk_mul_f32 v[78:79], v[70:71], v[80:81]
	v_max_f32_e32 v70, 0x1e3ce508, v3
	v_max_f32_e32 v3, v94, v94
	v_and_b32_e32 v95, 0xffff0000, v109
	v_max_f32_e32 v80, 0x1e3ce508, v3
	v_max_f32_e32 v3, v85, v85
	v_max_f32_e32 v71, 0x1e3ce508, v3
	v_max_f32_e32 v3, v95, v95
	v_max_f32_e32 v81, 0x1e3ce508, v3
	v_pk_mul_f32 v[76:77], v[76:77], v[70:71]
	v_pk_mul_f32 v[80:81], v[72:73], v[80:81]
	s_mov_b64 s[26:27], 0x90
	v_cvt_pk_bf16_f32 v70, v74, v75
	v_cvt_pk_bf16_f32 v71, v76, v77
	v_cvt_pk_bf16_f32 v72, v78, v79
	v_cvt_pk_bf16_f32 v73, v80, v81
	v_lshl_add_u64 v[80:81], v[184:185], 0, s[26:27]
	global_store_dwordx4 v[82:83], v[70:73], off offset:256
	s_waitcnt vmcnt(3)
	v_lshlrev_b32_e32 v3, 16, v86
	v_mad_u64_u32 v[70:71], s[26:27], v80, s83, v[146:147]
	v_mad_i32_i24 v71, v81, s83, v71
	v_lshl_add_u64 v[82:83], v[70:71], 0, v[4:5]
	v_add_co_u32_e32 v72, vcc, s71, v82
	v_lshl_add_u64 v[70:71], v[82:83], 0, s[28:29]
	s_nop 0
	v_addc_co_u32_e32 v73, vcc, 0, v83, vcc
	global_load_dwordx4 v[72:75], v[72:73], off
	s_nop 0
	global_load_dwordx4 v[76:79], v[70:71], off offset:256
	v_and_b32_e32 v85, 0xffff0000, v86
	v_lshlrev_b32_e32 v86, 16, v88
	v_max_f32_e32 v3, v3, v3
	v_max_f32_e32 v84, 0x1e3ce508, v3
	v_max_f32_e32 v3, v86, v86
	v_lshlrev_b32_e32 v94, 16, v87
	v_and_b32_e32 v95, 0xffff0000, v87
	v_and_b32_e32 v87, 0xffff0000, v88
	v_max_f32_e32 v86, 0x1e3ce508, v3
	v_max_f32_e32 v3, v85, v85
	v_max_f32_e32 v85, 0x1e3ce508, v3
	v_max_f32_e32 v3, v87, v87
	v_lshlrev_b32_e32 v88, 16, v89
	v_max_f32_e32 v87, 0x1e3ce508, v3
	v_max_f32_e32 v3, v94, v94
	v_pk_mul_f32 v[66:67], v[66:67], v[84:85]
	v_pk_mul_f32 v[84:85], v[62:63], v[86:87]
	v_max_f32_e32 v62, 0x1e3ce508, v3
	v_max_f32_e32 v3, v88, v88
	v_and_b32_e32 v89, 0xffff0000, v89
	v_max_f32_e32 v86, 0x1e3ce508, v3
	v_max_f32_e32 v3, v95, v95
	s_mov_b64 s[26:27], 0x80000
	v_max_f32_e32 v63, 0x1e3ce508, v3
	v_max_f32_e32 v3, v89, v89
	v_lshl_add_u64 v[70:71], v[148:149], 0, s[26:27]
	v_max_f32_e32 v87, 0x1e3ce508, v3
	v_pk_mul_f32 v[68:69], v[68:69], v[62:63]
	v_pk_mul_f32 v[86:87], v[64:65], v[86:87]
	v_cvt_pk_bf16_f32 v62, v66, v67
	v_lshl_add_u64 v[66:67], s[18:19], 0, v[70:71]
	v_cvt_pk_bf16_f32 v63, v68, v69
	v_cvt_pk_bf16_f32 v64, v84, v85
	v_cvt_pk_bf16_f32 v65, v86, v87
	v_lshl_add_u64 v[66:67], v[66:67], 0, v[4:5]
	s_waitcnt vmcnt(4)
	v_lshlrev_b32_e32 v3, 16, v90
	global_store_dwordx4 v[66:67], v[62:65], off
	v_max_f32_e32 v3, v3, v3
	v_lshlrev_b32_e32 v68, 16, v91
	v_lshlrev_b32_e32 v64, 16, v92
	v_and_b32_e32 v63, 0xffff0000, v90
	v_max_f32_e32 v62, 0x1e3ce508, v3
	v_max_f32_e32 v3, v64, v64
	v_and_b32_e32 v65, 0xffff0000, v92
	v_max_f32_e32 v64, 0x1e3ce508, v3
	v_max_f32_e32 v3, v63, v63
	v_max_f32_e32 v63, 0x1e3ce508, v3
	v_max_f32_e32 v3, v65, v65
	v_lshlrev_b32_e32 v84, 16, v93
	v_max_f32_e32 v65, 0x1e3ce508, v3
	v_max_f32_e32 v3, v68, v68
	v_and_b32_e32 v69, 0xffff0000, v91
	v_pk_mul_f32 v[58:59], v[58:59], v[62:63]
	v_pk_mul_f32 v[62:63], v[54:55], v[64:65]
	v_max_f32_e32 v54, 0x1e3ce508, v3
	v_max_f32_e32 v3, v84, v84
	v_and_b32_e32 v85, 0xffff0000, v93
	v_max_f32_e32 v64, 0x1e3ce508, v3
	v_max_f32_e32 v3, v69, v69
	v_max_f32_e32 v55, 0x1e3ce508, v3
	v_max_f32_e32 v3, v85, v85
	v_max_f32_e32 v65, 0x1e3ce508, v3
	v_pk_mul_f32 v[60:61], v[60:61], v[54:55]
	v_pk_mul_f32 v[64:65], v[56:57], v[64:65]
	v_cvt_pk_bf16_f32 v54, v58, v59
	v_cvt_pk_bf16_f32 v55, v60, v61
	v_cvt_pk_bf16_f32 v56, v62, v63
	v_cvt_pk_bf16_f32 v57, v64, v65
	s_mov_b32 s26, 0x32000
	global_store_dwordx4 v[66:67], v[54:57], off offset:256
	v_lshl_add_u64 v[58:59], v[82:83], 0, s[30:31]
	v_lshlrev_b64 v[62:63], 12, v[80:81]
	v_add_co_u32_e32 v54, vcc, s26, v82
	s_mov_b64 s[26:27], -1
	s_nop 0
	v_addc_co_u32_e32 v55, vcc, 0, v83, vcc
	s_waitcnt vmcnt(3)
	v_lshlrev_b32_e32 v3, 16, v72
	v_lshlrev_b32_e32 v66, 16, v74
	v_max_f32_e32 v3, v3, v3
	v_and_b32_e32 v65, 0xffff0000, v72
	v_max_f32_e32 v64, 0x1e3ce508, v3
	v_max_f32_e32 v3, v66, v66
	global_load_dwordx4 v[54:57], v[54:55], off
	s_nop 0
	global_load_dwordx4 v[58:61], v[58:59], off offset:256
	v_and_b32_e32 v67, 0xffff0000, v74
	v_max_f32_e32 v66, 0x1e3ce508, v3
	v_max_f32_e32 v3, v65, v65
	v_lshlrev_b32_e32 v68, 16, v73
	v_max_f32_e32 v65, 0x1e3ce508, v3
	v_max_f32_e32 v3, v67, v67
	v_lshlrev_b32_e32 v72, 16, v75
	v_max_f32_e32 v67, 0x1e3ce508, v3
	v_max_f32_e32 v3, v68, v68
	v_and_b32_e32 v69, 0xffff0000, v73
	v_pk_mul_f32 v[50:51], v[50:51], v[64:65]
	v_pk_mul_f32 v[64:65], v[46:47], v[66:67]
	v_max_f32_e32 v46, 0x1e3ce508, v3
	v_max_f32_e32 v3, v72, v72
	v_and_b32_e32 v73, 0xffff0000, v75
	v_max_f32_e32 v66, 0x1e3ce508, v3
	v_max_f32_e32 v3, v69, v69
	v_max_f32_e32 v47, 0x1e3ce508, v3
	v_max_f32_e32 v3, v73, v73
	v_max_f32_e32 v67, 0x1e3ce508, v3
	v_pk_mul_f32 v[52:53], v[52:53], v[46:47]
	v_pk_mul_f32 v[66:67], v[48:49], v[66:67]
	v_cvt_pk_bf16_f32 v46, v50, v51
	v_lshl_add_u64 v[50:51], s[18:19], 0, v[62:63]
	v_cvt_pk_bf16_f32 v47, v52, v53
	v_cvt_pk_bf16_f32 v48, v64, v65
	v_cvt_pk_bf16_f32 v49, v66, v67
	v_lshl_add_u64 v[50:51], v[50:51], 0, v[4:5]
	s_waitcnt vmcnt(4)
; __device__ __forceinline__ unsigned cvt_pk_bf16(float lo, float hi) { const f2_t_ v = {lo, hi}; return __builtin_bit_cast(unsigned, __builtin_convertvector(v, bf2_t_)); }
;     static __device__ __forceinline__ void unpack(const u32x4 g4, f32x4& g0, f32x4& g1) { g0 = (f32x4){bflo(g4.x), bfhi(g4.x), bflo(g4.y), bfhi(g4.y)}; g1 = (f32x4){bflo(g4.z), bfhi(g4.z), bflo(g4.w), bfhi(g4.w)}; }
;     __device__ __forceinline__ void operator()(const f32x4 (&acc)[2][2][4][2], const Unit& u, int wr, int wc, int fr, int fq) const {
;     ...
;             if (gi < 7) { const size_t row2 = r0 + ((gi + 1) >> 2) * HALF + ((gi + 1) & 3) * 16;
; #pragma unroll
;                 for (int bj = 0; bj < 2; ++bj) gw[(gi + 1) & 1][bj] = *(const u32x4*)(GT + row2 * ldg + 4096 + col0 + bj * HALF); }
;             asm volatile("" ::: "memory");
; #pragma unroll
;             for (int bj = 0; bj < 2; ++bj) {
;                 f32x4 g0, g1; unpack(gw[gi & 1][bj], g0, g1);
;                 f32x4 v0, v1;
; #pragma unroll
;                 for (int j = 0; j < 4; ++j) { v0[j] = acc[ai][bj][m][0][j] * fmaxf(g0[j], 1e-20f); v1[j] = acc[ai][bj][m][1][j] * fmaxf(g1[j], 1e-20f); }
;                 u32x4 w; w.x = cvt_pk_bf16(v0[0], v0[1]); w.y = cvt_pk_bf16(v0[2], v0[3]); w.z = cvt_pk_bf16(v1[0], v1[1]); w.w = cvt_pk_bf16(v1[2], v1[3]);
;                 *(u32x4*)(O + row * 2048 + col0 + bj * HALF) = w;
;             }
	v_lshlrev_b32_e32 v3, 16, v76
	global_store_dwordx4 v[50:51], v[46:49], off
	v_max_f32_e32 v3, v3, v3
	v_lshlrev_b32_e32 v52, 16, v77
	v_lshlrev_b32_e32 v48, 16, v78
	v_and_b32_e32 v47, 0xffff0000, v76
	v_max_f32_e32 v46, 0x1e3ce508, v3
	v_max_f32_e32 v3, v48, v48
	v_and_b32_e32 v49, 0xffff0000, v78
	v_max_f32_e32 v48, 0x1e3ce508, v3
	v_max_f32_e32 v3, v47, v47
	v_max_f32_e32 v47, 0x1e3ce508, v3
	v_max_f32_e32 v3, v49, v49
	v_lshlrev_b32_e32 v62, 16, v79
	v_max_f32_e32 v49, 0x1e3ce508, v3
	v_max_f32_e32 v3, v52, v52
	v_and_b32_e32 v53, 0xffff0000, v77
	v_pk_mul_f32 v[42:43], v[42:43], v[46:47]
	v_pk_mul_f32 v[46:47], v[38:39], v[48:49]
	v_max_f32_e32 v38, 0x1e3ce508, v3
	v_max_f32_e32 v3, v62, v62
	v_and_b32_e32 v63, 0xffff0000, v79
	v_max_f32_e32 v48, 0x1e3ce508, v3
	v_max_f32_e32 v3, v53, v53
	v_max_f32_e32 v39, 0x1e3ce508, v3
	v_max_f32_e32 v3, v63, v63
	v_max_f32_e32 v49, 0x1e3ce508, v3
	v_pk_mul_f32 v[44:45], v[44:45], v[38:39]
	v_pk_mul_f32 v[48:49], v[40:41], v[48:49]
	v_cvt_pk_bf16_f32 v38, v42, v43
	v_cvt_pk_bf16_f32 v39, v44, v45
	v_cvt_pk_bf16_f32 v40, v46, v47
	v_cvt_pk_bf16_f32 v41, v48, v49
	global_store_dwordx4 v[50:51], v[38:41], off offset:256
	v_lshl_add_u64 v[42:43], v[82:83], 0, s[60:61]
	v_or_b32_e32 v46, 0x20000, v70
	v_add_co_u32_e32 v38, vcc, s73, v82
	v_mov_b32_e32 v47, v71
	s_nop 0
	v_addc_co_u32_e32 v39, vcc, 0, v83, vcc
	global_load_dwordx4 v[38:41], v[38:39], off
	s_nop 0
	global_load_dwordx4 v[42:45], v[42:43], off offset:256
	v_or_b32_e32 v70, 0x30000, v70
	s_and_b64 vcc, exec, s[2:3]
	s_waitcnt vmcnt(5)
	v_lshlrev_b32_e32 v3, 16, v54
	v_lshlrev_b32_e32 v50, 16, v56
	v_max_f32_e32 v3, v3, v3
	v_and_b32_e32 v49, 0xffff0000, v54
	v_max_f32_e32 v48, 0x1e3ce508, v3
	v_max_f32_e32 v3, v50, v50
	v_and_b32_e32 v51, 0xffff0000, v56
	v_max_f32_e32 v50, 0x1e3ce508, v3
	v_max_f32_e32 v3, v49, v49
	v_lshlrev_b32_e32 v52, 16, v55
	v_max_f32_e32 v49, 0x1e3ce508, v3
	v_max_f32_e32 v3, v51, v51
	v_lshlrev_b32_e32 v54, 16, v57
	v_max_f32_e32 v51, 0x1e3ce508, v3
	v_max_f32_e32 v3, v52, v52
	v_and_b32_e32 v53, 0xffff0000, v55
	v_pk_mul_f32 v[34:35], v[34:35], v[48:49]
	v_pk_mul_f32 v[48:49], v[30:31], v[50:51]
	v_max_f32_e32 v30, 0x1e3ce508, v3
	v_max_f32_e32 v3, v54, v54
	v_and_b32_e32 v55, 0xffff0000, v57
	v_max_f32_e32 v50, 0x1e3ce508, v3
	v_max_f32_e32 v3, v53, v53
	v_max_f32_e32 v31, 0x1e3ce508, v3
	v_max_f32_e32 v3, v55, v55
	v_max_f32_e32 v51, 0x1e3ce508, v3
	v_pk_mul_f32 v[36:37], v[36:37], v[30:31]
	v_pk_mul_f32 v[50:51], v[32:33], v[50:51]
	v_cvt_pk_bf16_f32 v30, v34, v35
	v_lshl_add_u64 v[34:35], s[18:19], 0, v[46:47]
	v_cvt_pk_bf16_f32 v31, v36, v37
	v_cvt_pk_bf16_f32 v32, v48, v49
	v_cvt_pk_bf16_f32 v33, v50, v51
	v_lshl_add_u64 v[34:35], v[34:35], 0, v[4:5]
	s_waitcnt vmcnt(4)
	v_lshlrev_b32_e32 v3, 16, v58
	global_store_dwordx4 v[34:35], v[30:33], off
	v_max_f32_e32 v3, v3, v3
	v_lshlrev_b32_e32 v36, 16, v59
	v_lshlrev_b32_e32 v32, 16, v60
	v_and_b32_e32 v31, 0xffff0000, v58
	v_max_f32_e32 v30, 0x1e3ce508, v3
	v_max_f32_e32 v3, v32, v32
	v_and_b32_e32 v33, 0xffff0000, v60
	v_max_f32_e32 v32, 0x1e3ce508, v3
	v_max_f32_e32 v3, v31, v31
	v_max_f32_e32 v31, 0x1e3ce508, v3
	v_max_f32_e32 v3, v33, v33
	v_lshlrev_b32_e32 v46, 16, v61
	v_max_f32_e32 v33, 0x1e3ce508, v3
	v_max_f32_e32 v3, v36, v36
	v_and_b32_e32 v37, 0xffff0000, v59
	v_pk_mul_f32 v[26:27], v[26:27], v[30:31]
	v_pk_mul_f32 v[30:31], v[22:23], v[32:33]
	v_max_f32_e32 v22, 0x1e3ce508, v3
	v_max_f32_e32 v3, v46, v46
	v_and_b32_e32 v47, 0xffff0000, v61
	v_max_f32_e32 v32, 0x1e3ce508, v3
	v_max_f32_e32 v3, v37, v37
	v_max_f32_e32 v23, 0x1e3ce508, v3
	v_max_f32_e32 v3, v47, v47
	v_max_f32_e32 v33, 0x1e3ce508, v3
	v_pk_mul_f32 v[28:29], v[28:29], v[22:23]
	v_pk_mul_f32 v[32:33], v[24:25], v[32:33]
	v_cvt_pk_bf16_f32 v22, v26, v27
	v_cvt_pk_bf16_f32 v23, v28, v29
	v_cvt_pk_bf16_f32 v24, v30, v31
	v_cvt_pk_bf16_f32 v25, v32, v33
	global_store_dwordx4 v[34:35], v[22:25], off offset:256
	s_waitcnt vmcnt(3)
	v_lshlrev_b32_e32 v3, 16, v38
	s_nop 0
	v_lshlrev_b32_e32 v24, 16, v40
	v_max_f32_e32 v3, v3, v3
	v_and_b32_e32 v23, 0xffff0000, v38
	v_max_f32_e32 v22, 0x1e3ce508, v3
	v_max_f32_e32 v3, v24, v24
	v_and_b32_e32 v25, 0xffff0000, v40
	v_max_f32_e32 v24, 0x1e3ce508, v3
	v_max_f32_e32 v3, v23, v23
	v_lshlrev_b32_e32 v26, 16, v39
	v_max_f32_e32 v23, 0x1e3ce508, v3
	v_max_f32_e32 v3, v25, v25
	v_lshlrev_b32_e32 v28, 16, v41
	v_max_f32_e32 v25, 0x1e3ce508, v3
	v_max_f32_e32 v3, v26, v26
	v_and_b32_e32 v27, 0xffff0000, v39
	v_pk_mul_f32 v[18:19], v[18:19], v[22:23]
	v_pk_mul_f32 v[22:23], v[14:15], v[24:25]
	v_max_f32_e32 v14, 0x1e3ce508, v3
	v_max_f32_e32 v3, v28, v28
	v_and_b32_e32 v29, 0xffff0000, v41
	v_max_f32_e32 v24, 0x1e3ce508, v3
	v_max_f32_e32 v3, v27, v27
	v_max_f32_e32 v15, 0x1e3ce508, v3
	v_max_f32_e32 v3, v29, v29
	v_max_f32_e32 v25, 0x1e3ce508, v3
	v_pk_mul_f32 v[20:21], v[20:21], v[14:15]
	v_pk_mul_f32 v[24:25], v[16:17], v[24:25]
	v_cvt_pk_bf16_f32 v14, v18, v19
	v_lshl_add_u64 v[18:19], s[18:19], 0, v[70:71]
	v_cvt_pk_bf16_f32 v15, v20, v21
	v_cvt_pk_bf16_f32 v16, v22, v23
	v_cvt_pk_bf16_f32 v17, v24, v25
	v_lshl_add_u64 v[18:19], v[18:19], 0, v[4:5]
	s_waitcnt vmcnt(2)
	v_lshlrev_b32_e32 v3, 16, v42
	global_store_dwordx4 v[18:19], v[14:17], off
	v_max_f32_e32 v3, v3, v3
	v_and_b32_e32 v5, 0xffff0000, v42
	v_lshlrev_b32_e32 v14, 16, v44
	v_max_f32_e32 v4, 0x1e3ce508, v3
	v_max_f32_e32 v3, v14, v14
	v_and_b32_e32 v15, 0xffff0000, v44
	v_max_f32_e32 v14, 0x1e3ce508, v3
	v_max_f32_e32 v3, v5, v5
	v_lshlrev_b32_e32 v16, 16, v43
	v_max_f32_e32 v5, 0x1e3ce508, v3
	v_max_f32_e32 v3, v15, v15
	v_lshlrev_b32_e32 v20, 16, v45
	v_max_f32_e32 v15, 0x1e3ce508, v3
	v_max_f32_e32 v3, v16, v16
	v_and_b32_e32 v17, 0xffff0000, v43
	v_pk_mul_f32 v[4:5], v[10:11], v[4:5]
	v_max_f32_e32 v10, 0x1e3ce508, v3
	v_max_f32_e32 v3, v20, v20
	v_and_b32_e32 v21, 0xffff0000, v45
	v_pk_mul_f32 v[6:7], v[6:7], v[14:15]
	v_max_f32_e32 v14, 0x1e3ce508, v3
	v_max_f32_e32 v3, v17, v17
	v_max_f32_e32 v11, 0x1e3ce508, v3
	v_max_f32_e32 v3, v21, v21
	v_max_f32_e32 v15, 0x1e3ce508, v3
	v_pk_mul_f32 v[10:11], v[12:13], v[10:11]
	v_pk_mul_f32 v[8:9], v[8:9], v[14:15]
	v_cvt_pk_bf16_f32 v4, v4, v5
	v_cvt_pk_bf16_f32 v5, v10, v11
	v_cvt_pk_bf16_f32 v6, v6, v7
	v_cvt_pk_bf16_f32 v7, v8, v9
	global_store_dwordx4 v[18:19], v[4:7], off offset:256
	s_cbranch_vccnz .LBB0_980
	s_andn2_b64 vcc, exec, s[14:15]
	s_cbranch_vccnz .LBB0_979
	s_barrier
	s_branch .LBB0_979
